# previous split-26 version + retention scan inter-chunk MFMA section with pipelined LDS fragment reads
# speedup vs baseline: 1.0483x; 1.0062x over previous
; #define MFMA(a, b, c) __builtin_amdgcn_mfma_f32_32x32x16_bf16((a), (b), (c), 0, 0, 0)
; template <bool ML>
; DI void scan_block(const Params& p, int sitem, char* smem) {
;     ...
;       {
;         const bfu* qa = qS + l32 * LQ + 4 * hi; const bfu* qb = qa + 32 * LQ;
; #pragma unroll
;         for (int i = 0; i < 4; ++i)
; #pragma unroll
;           for (int s2 = 0; s2 < 2; ++s2) {
;             const bf16x8 cf = packacc(C[i], s2);
;             out0 = MFMA(cf, ld44(qa + 32 * i + 16 * s2), out0);
;             out1 = MFMA(cf, ld44(qb + 32 * i + 16 * s2), out1);
;           }
;       }
;       {
;         const float sct0 = wsm[128 + l32], sct1 = wsm[160 + l32];
; #pragma unroll
;         for (int r = 0; r < 16; ++r) { out0[r] *= sct0; out1[r] *= sct1; }
;       }
;       const bfu* v0 = vTS + (w * 32 + l32) * LT + 4 * hi; const bfu* v1 = v0 + 32;
;       const float sB0 = wsm[l32], sB1 = wsm[32 + l32];
;       {
;         f32x16 sd0, sx;
; #pragma unroll
;         for (int r = 0; r < 16; ++r) { sd0[r] = 0.f; sx[r] = 0.f; }
.LBB0_1463:
	s_waitcnt lgkmcnt(0)
	s_barrier
	v_add_u32_e32 v104, 0x2000, v196
	ds_read2_b64 v[100:103], v196 offset1:2
	ds_read2_b64 v[108:111], v104 offset0:64 offset1:66
	ds_read2_b64 v[112:115], v196 offset0:4 offset1:6
	ds_read2_b64 v[116:119], v104 offset0:68 offset1:70
	ds_read2_b64 v[120:123], v196 offset0:8 offset1:10
	ds_read2_b64 v[124:127], v104 offset0:72 offset1:74
	v_cvt_pk_bf16_f32 v96, v48, v49
	v_cvt_pk_bf16_f32 v97, v50, v51
	v_cvt_pk_bf16_f32 v98, v52, v53
	v_cvt_pk_bf16_f32 v99, v54, v55
	s_mov_b32 s40, 8
	v_add_u32_e32 v243, v196, v165
	s_waitcnt lgkmcnt(5)
	s_nop 0
	v_mfma_f32_32x32x16_bf16 v[80:95], v[96:99], v[100:103], 0
	s_waitcnt lgkmcnt(4)
	v_mfma_f32_32x32x16_bf16 v[64:79], v[96:99], v[108:111], 0
	ds_read2_b64 v[100:103], v196 offset0:12 offset1:14
	ds_read2_b64 v[108:111], v104 offset0:76 offset1:78
	v_cvt_pk_bf16_f32 v96, v56, v57
	v_cvt_pk_bf16_f32 v97, v58, v59
	v_cvt_pk_bf16_f32 v98, v60, v61
	v_cvt_pk_bf16_f32 v99, v62, v63
	s_waitcnt lgkmcnt(5)
	s_nop 0
	v_mfma_f32_32x32x16_bf16 v[80:95], v[96:99], v[112:115], v[80:95]
	s_waitcnt lgkmcnt(4)
	v_mfma_f32_32x32x16_bf16 v[64:79], v[96:99], v[116:119], v[64:79]
	ds_read2_b64 v[112:115], v196 offset0:16 offset1:18
	ds_read2_b64 v[116:119], v104 offset0:80 offset1:82
	v_cvt_pk_bf16_f32 v96, v32, v33
	v_cvt_pk_bf16_f32 v97, v34, v35
	v_cvt_pk_bf16_f32 v98, v36, v37
	v_cvt_pk_bf16_f32 v99, v38, v39
	s_waitcnt lgkmcnt(5)
	s_nop 0
	v_mfma_f32_32x32x16_bf16 v[80:95], v[96:99], v[120:123], v[80:95]
	s_waitcnt lgkmcnt(4)
	v_mfma_f32_32x32x16_bf16 v[64:79], v[96:99], v[124:127], v[64:79]
	ds_read2_b64 v[120:123], v196 offset0:20 offset1:22
	ds_read2_b64 v[124:127], v104 offset0:84 offset1:86
	v_cvt_pk_bf16_f32 v96, v40, v41
	v_cvt_pk_bf16_f32 v97, v42, v43
	v_cvt_pk_bf16_f32 v98, v44, v45
	v_cvt_pk_bf16_f32 v99, v46, v47
	s_waitcnt lgkmcnt(5)
	s_nop 0
	v_mfma_f32_32x32x16_bf16 v[80:95], v[96:99], v[100:103], v[80:95]
	s_waitcnt lgkmcnt(4)
	v_mfma_f32_32x32x16_bf16 v[64:79], v[96:99], v[108:111], v[64:79]
	ds_read2_b64 v[100:103], v196 offset0:24 offset1:26
	ds_read2_b64 v[108:111], v104 offset0:88 offset1:90
	v_cvt_pk_bf16_f32 v96, v16, v17
	v_cvt_pk_bf16_f32 v97, v18, v19
	v_cvt_pk_bf16_f32 v98, v20, v21
	v_cvt_pk_bf16_f32 v99, v22, v23
	s_waitcnt lgkmcnt(5)
	s_nop 0
	v_mfma_f32_32x32x16_bf16 v[80:95], v[96:99], v[112:115], v[80:95]
	s_waitcnt lgkmcnt(4)
	v_mfma_f32_32x32x16_bf16 v[64:79], v[96:99], v[116:119], v[64:79]
	ds_read2_b64 v[112:115], v196 offset0:28 offset1:30
	ds_read2_b64 v[116:119], v104 offset0:92 offset1:94
	v_cvt_pk_bf16_f32 v96, v24, v25
	v_cvt_pk_bf16_f32 v97, v26, v27
	v_cvt_pk_bf16_f32 v98, v28, v29
	v_cvt_pk_bf16_f32 v99, v30, v31
	s_waitcnt lgkmcnt(5)
	s_nop 0
	v_mfma_f32_32x32x16_bf16 v[80:95], v[96:99], v[120:123], v[80:95]
	s_waitcnt lgkmcnt(4)
	v_mfma_f32_32x32x16_bf16 v[64:79], v[96:99], v[124:127], v[64:79]
	v_cvt_pk_bf16_f32 v96, v0, v1
	v_cvt_pk_bf16_f32 v97, v2, v3
	v_cvt_pk_bf16_f32 v98, v4, v5
	v_cvt_pk_bf16_f32 v99, v6, v7
	s_waitcnt lgkmcnt(3)
	s_nop 0
	v_mfma_f32_32x32x16_bf16 v[80:95], v[96:99], v[100:103], v[80:95]
	s_waitcnt lgkmcnt(2)
	v_mfma_f32_32x32x16_bf16 v[64:79], v[96:99], v[108:111], v[64:79]
	v_cvt_pk_bf16_f32 v96, v8, v9
	v_cvt_pk_bf16_f32 v97, v10, v11
	v_cvt_pk_bf16_f32 v98, v12, v13
	v_cvt_pk_bf16_f32 v99, v14, v15
	ds_read2st64_b32 v[192:193], v197 offset1:2
	ds_read_b32 v190, v197 offset:640
	ds_read_b32 v242, v199
	s_waitcnt lgkmcnt(4)
	s_nop 0
	v_mfma_f32_32x32x16_bf16 v[80:95], v[96:99], v[112:115], v[80:95]
	s_waitcnt lgkmcnt(0)
	v_mfma_f32_32x32x16_bf16 v[64:79], v[96:99], v[116:119], v[64:79]
	v_mov_b32_e32 v96, 0
	v_mov_b32_e32 v97, v96
	v_mov_b32_e32 v98, v96
	v_mov_b32_e32 v99, v96
	v_mov_b32_e32 v100, v96
	v_mov_b32_e32 v101, v96
	v_mov_b32_e32 v102, v96
	v_mov_b32_e32 v103, v96
	v_mov_b32_e32 v104, v96
	v_mov_b32_e32 v105, v96
	v_mov_b32_e32 v106, v96
	v_mov_b32_e32 v107, v96
	v_mov_b32_e32 v108, v96
	v_mov_b32_e32 v109, v96
	v_mov_b32_e32 v110, v96
	v_mov_b32_e32 v111, v96
	v_mov_b32_e32 v112, v96
	v_mov_b32_e32 v113, v96
	v_mov_b32_e32 v114, v96
	v_mov_b32_e32 v115, v96
	v_mov_b32_e32 v116, v96
	v_mov_b32_e32 v117, v96
	v_mov_b32_e32 v118, v96
	v_mov_b32_e32 v119, v96
	v_mov_b32_e32 v120, v96
	v_mov_b32_e32 v121, v96
	v_mov_b32_e32 v122, v96
	v_mov_b32_e32 v123, v96
	v_mov_b32_e32 v124, v96
	v_mov_b32_e32 v125, v96
	v_mov_b32_e32 v126, v96
	v_mov_b32_e32 v127, v96
